# v34 + MLA epilogue z wait skipped when the look-ahead counter snapshot already shows the block's z tiles
# speedup vs baseline: 1.0063x; 1.0040x over previous
.LBB0_354:
	s_or_b64 exec, exec, s[28:29]
	s_andn2_b64 vcc, exec, s[12:13]
	s_cbranch_vccnz .Lmz_done
	s_ashr_i32 s101, s5, 8
	s_add_i32 s101, s101, 32
	s_nop 3
	v_readlane_b32 s100, v178, s101
	s_cmp_gt_u32 s100, 3
	s_cbranch_scc1 .Lmz_done
	s_ashr_i32 s100, s5, 8
	s_add_i32 s100, s100, s79
	s_lshl_b32 s100, s100, 4
	v_readlane_b32 s101, v255, 10
	s_add_u32 s100, s101, s100
	v_readlane_b32 s101, v255, 11
	s_addc_u32 s101, s101, 0
	v_mov_b32_e32 v176, s100
	v_mov_b32_e32 v177, s101
	s_movk_i32 s100, 0
